# GEMM K loops: static priority raise for waves 0-3 instead of per-segment toggling
# baseline (speedup 1.0000x reference)
.LBB0_1023:
	v_readfirstlane_b32 s98, v246
	s_cmpk_ge_u32 s98, 0x100
	s_cbranch_scc1 .Lsp_skip_1024
	s_setprio 1
